# norm-weight hoist also on the layer-0 input norm (f32 rows -> H and U) row loop
# baseline (speedup 1.0000x reference)
; __device__ __forceinline__ void store8_wt(void* p, u32x2w v) { asm volatile("global_store_dwordx2 %0, %1, off sc1\n\ts_nop 1" :: "v"(p), "v"(v) : "memory"); }
; __device__ __forceinline__ unsigned pk2(float lo, float hi) { f32x2_t v = {lo, hi}; bf16x2_t b = __builtin_convertvector(v, bf16x2_t); return __builtin_bit_cast(unsigned, b); }
; template <int MODE> __device__ __forceinline__ void norm_phase(const Ptrs& P, const float* nw, int gw, int NGW, int lane) {
;     ...
;     int row = gw;
;     if (row < nrows) NORM_LOAD(row);
;     for (; row < nrows; row += NGW) {
;         f32x4 v[8]; float ss = 0.f;
; #pragma unroll
;         for (int j = 0; j < 8; ++j) v[j] = (MODE == 1) ? xn[j] : (f32x4){bflo(hn[j].x), bfhi(hn[j].x), bflo(hn[j].y), bfhi(hn[j].y)};
;         if (row + NGW < nrows) NORM_LOAD(row + NGW);
; #pragma unroll
;         for (int j = 0; j < 8; ++j) ss += (v[j][0] * v[j][0] + v[j][1] * v[j][1]) + (v[j][2] * v[j][2] + v[j][3] * v[j][3]);
;         ss = wave_sum(ss, lane);
;         const float rstd = 1.0f / sqrtf(ss * (1.0f / DM) + EPS);
;         if (MODE == 1) {
; #pragma unroll
;             for (int j = 0; j < 8; ++j) { u32x2 w; w.x = pk2(v[j][0], v[j][1]); w.y = pk2(v[j][2], v[j][3]); pg8::store8_wt((u32x2*)(H + (size_t)row * DM) + 64 * j + lane, w); }
;         }
; #pragma unroll
;         for (int j = 0; j < 8; ++j) {
;             const f32x4 w4 = ((const f32x4*)nw)[64 * j + lane];
.LBB0_151:
	s_or_b64 exec, exec, s[6:7]
	v_lshlrev_b32_e32 v32, 4, v30
	v_mov_b32_e32 v33, v16
	v_lshl_add_u64 v[4:5], v[4:5], 0, v[32:33]
	v_add_co_u32_e32 v6, vcc, 0x1000, v4
	global_load_dwordx4 v[22:25], v[4:5], off offset:3072
	global_load_dwordx4 v[42:45], v[4:5], off offset:2048
	global_load_dwordx4 v[62:65], v[4:5], off offset:1024
	global_load_dwordx4 v[66:69], v[4:5], off
	v_addc_co_u32_e32 v7, vcc, 0, v5, vcc
	global_load_dwordx4 v[18:21], v[6:7], off
	global_load_dwordx4 v[12:15], v[6:7], off offset:1024
	global_load_dwordx4 v[8:11], v[6:7], off offset:2048
	s_nop 0
	global_load_dwordx4 v[4:7], v[6:7], off offset:3072
	v_readlane_b32 s3, v255, 17
	v_or_b32_e32 v34, 0x100, v30
	v_or_b32_e32 v36, 0x140, v30
	v_lshl_add_u32 v94, v17, 11, s3
	v_readlane_b32 s3, v255, 19
	v_or_b32_e32 v38, 0x180, v30
	v_or_b32_e32 v40, 0x1c0, v30
	v_lshlrev_b64 v[54:55], 12, v[70:71]
	v_add_u32_e32 v56, s3, v17
	v_mov_b32_e32 v47, v16
	v_mov_b32_e32 v49, v16
	v_mov_b32_e32 v51, v16
	v_mov_b32_e32 v53, v16
	v_lshlrev_b32_e32 v46, 4, v34
	v_lshlrev_b32_e32 v48, 4, v36
	v_lshlrev_b32_e32 v50, 4, v38
	v_lshlrev_b32_e32 v52, 4, v40
	v_lshl_or_b32 v54, v30, 3, v54
	v_ashrrev_i32_e32 v57, 31, v56
	v_lshlrev_b32_e32 v31, 2, v30
	s_waitcnt vmcnt(10)
	v_lshl_add_u64 v[74:75], v[26:27], 0, v[32:33]
	v_lshl_add_u64 v[84:85], v[26:27], 0, v[46:47]
	v_lshl_add_u64 v[86:87], v[26:27], 0, v[48:49]
	v_lshl_add_u64 v[88:89], v[26:27], 0, v[50:51]
	v_lshl_add_u64 v[90:91], v[26:27], 0, v[52:53]
	s_waitcnt vmcnt(9)
	v_lshl_add_u64 v[26:27], v[28:29], 0, v[54:55]
	v_lshlrev_b64 v[28:29], 13, v[56:57]
	s_mov_b64 s[8:9], 0x10300000
	v_lshlrev_b32_e32 v72, 4, v30
	v_xor_b32_e32 v17, 4, v31
	v_xor_b32_e32 v71, 8, v31
	v_xor_b32_e32 v95, 16, v31
	v_xor_b32_e32 v96, 32, v31
	v_xor_b32_e32 v97, 64, v31
	v_xor_b32_e32 v98, 0x80, v31
	v_lshlrev_b32_e32 v76, 4, v34
	v_lshlrev_b32_e32 v78, 4, v36
	v_lshlrev_b32_e32 v80, 4, v38
	v_lshlrev_b32_e32 v82, 4, v40
	v_lshl_add_u64 v[92:93], v[26:27], 0, s[8:9]
	s_waitcnt vmcnt(8)
	v_lshl_add_u64 v[0:1], v[0:1], 0, v[28:29]
	s_mov_b64 s[6:7], 0
	s_waitcnt vmcnt(7)
	v_mov_b64_e32 v[40:41], v[24:25]
	s_waitcnt vmcnt(6)
	v_mov_b64_e32 v[34:35], v[42:43]
	s_waitcnt vmcnt(5)
	v_mov_b64_e32 v[30:31], v[62:63]
	s_waitcnt vmcnt(4)
	v_mov_b64_e32 v[26:27], v[66:67]
	s_waitcnt vmcnt(3)
	v_mov_b64_e32 v[48:49], v[20:21]
	s_waitcnt vmcnt(2)
	v_mov_b64_e32 v[52:53], v[14:15]
	s_waitcnt vmcnt(1)
	v_mov_b64_e32 v[56:57], v[10:11]
	s_waitcnt vmcnt(0)
	v_mov_b64_e32 v[60:61], v[6:7]
	v_mov_b64_e32 v[28:29], v[68:69]
	v_mov_b64_e32 v[32:33], v[64:65]
	v_mov_b64_e32 v[36:37], v[44:45]
	v_mov_b64_e32 v[38:39], v[22:23]
	v_mov_b64_e32 v[46:47], v[18:19]
	v_mov_b64_e32 v[50:51], v[12:13]
	v_mov_b64_e32 v[54:55], v[8:9]
	v_mov_b64_e32 v[58:59], v[4:5]
	global_load_dwordx4 v[128:131], v[74:75], off
	global_load_dwordx4 v[132:135], v[74:75], off offset:1024
	global_load_dwordx4 v[136:139], v[74:75], off offset:2048
	global_load_dwordx4 v[140:143], v[74:75], off offset:3072
	global_load_dwordx4 v[144:147], v[84:85], off
	global_load_dwordx4 v[148:151], v[86:87], off
	global_load_dwordx4 v[152:155], v[88:89], off
	global_load_dwordx4 v[156:159], v[90:91], off
	s_waitcnt vmcnt(0)
	s_branch .LBB0_154

; __device__ __forceinline__ void store8_wt(void* p, u32x2w v) { asm volatile("global_store_dwordx2 %0, %1, off sc1\n\ts_nop 1" :: "v"(p), "v"(v) : "memory"); }
; __device__ __forceinline__ unsigned pk2(float lo, float hi) { f32x2_t v = {lo, hi}; bf16x2_t b = __builtin_convertvector(v, bf16x2_t); return __builtin_bit_cast(unsigned, b); }
; template <int MODE> __device__ __forceinline__ void norm_phase(const Ptrs& P, const float* nw, int gw, int NGW, int lane) {
;     ...
;         f32x4 v[8]; float ss = 0.f;
; #pragma unroll
;         for (int j = 0; j < 8; ++j) v[j] = (MODE == 1) ? xn[j] : (f32x4){bflo(hn[j].x), bfhi(hn[j].x), bflo(hn[j].y), bfhi(hn[j].y)};
;         if (row + NGW < nrows) NORM_LOAD(row + NGW);
; #pragma unroll
;         for (int j = 0; j < 8; ++j) ss += (v[j][0] * v[j][0] + v[j][1] * v[j][1]) + (v[j][2] * v[j][2] + v[j][3] * v[j][3]);
;         ss = wave_sum(ss, lane);
;         const float rstd = 1.0f / sqrtf(ss * (1.0f / DM) + EPS);
;         if (MODE == 1) {
; #pragma unroll
;             for (int j = 0; j < 8; ++j) { u32x2 w; w.x = pk2(v[j][0], v[j][1]); w.y = pk2(v[j][2], v[j][3]); pg8::store8_wt((u32x2*)(H + (size_t)row * DM) + 64 * j + lane, w); }
.LBB0_153:
	s_or_b64 exec, exec, s[8:9]
	v_mov_b32_e32 v102, v63
	v_mov_b32_e32 v103, v67
	v_mov_b32_e32 v106, v65
	v_mov_b32_e32 v107, v69
	v_mov_b32_e32 v100, v62
	v_mov_b32_e32 v101, v66
	v_pk_mul_f32 v[102:103], v[102:103], v[102:103]
	v_mov_b32_e32 v104, v64
	v_mov_b32_e32 v105, v68
	v_pk_mul_f32 v[106:107], v[106:107], v[106:107]
	v_pk_fma_f32 v[100:101], v[100:101], v[100:101], v[102:103]
	v_pk_fma_f32 v[102:103], v[104:105], v[104:105], v[106:107]
	v_pk_mul_f32 v[104:105], v[42:43], v[42:43]
	v_pk_add_f32 v[100:101], v[100:101], v[102:103]
	v_pk_mul_f32 v[102:103], v[44:45], v[44:45]
	v_pk_add_f32 v[100:101], v[100:101], v[100:101] op_sel_hi:[0,1]
	v_mov_b32_e32 v106, v104
	v_mov_b32_e32 v107, v103
	v_pk_mov_b32 v[102:103], v[104:105], v[102:103] op_sel:[1,0]
	v_mul_f32_e32 v100, v22, v22
	v_pk_add_f32 v[102:103], v[102:103], v[106:107]
	v_pk_fma_f32 v[104:105], v[22:23], v[22:23], v[100:101] op_sel_hi:[1,1,0]
	v_mul_f32_e32 v100, v24, v24
	v_pk_add_f32 v[102:103], v[102:103], v[102:103] op_sel_hi:[0,1]
	v_pk_fma_f32 v[106:107], v[24:25], v[24:25], v[100:101] op_sel_hi:[1,1,0]
	v_mul_f32_e32 v104, v18, v18
	v_mul_f32_e32 v106, v19, v19
	v_mul_f32_e32 v102, v20, v20
	v_mul_f32_e32 v100, v21, v21
	v_pk_add_f32 v[104:105], v[104:105], v[106:107]
	v_pk_add_f32 v[100:101], v[102:103], v[100:101]
	v_pk_mul_f32 v[102:103], v[12:13], v[12:13]
	v_pk_add_f32 v[100:101], v[104:105], v[100:101]
	v_mov_b32_e32 v106, v102
	v_pk_add_f32 v[104:105], v[100:101], v[100:101] op_sel_hi:[0,1]
	v_pk_mul_f32 v[100:101], v[14:15], v[14:15]
	s_and_b64 s[8:9], exec, vcc
	v_mov_b32_e32 v107, v101
	v_pk_mov_b32 v[100:101], v[102:103], v[100:101] op_sel:[1,0]
	s_or_b64 s[6:7], s[8:9], s[6:7]
	v_pk_add_f32 v[100:101], v[100:101], v[106:107]
	s_mov_b32 s8, 0xefe00000
	v_pk_add_f32 v[106:107], v[100:101], v[100:101] op_sel_hi:[0,1]
	v_mul_f32_e32 v100, v8, v8
	v_pk_fma_f32 v[108:109], v[8:9], v[8:9], v[100:101] op_sel_hi:[1,1,0]
	v_mul_f32_e32 v100, v10, v10
	s_mov_b32 s9, -1
	v_pk_fma_f32 v[110:111], v[10:11], v[10:11], v[100:101] op_sel_hi:[1,1,0]
	v_lshl_add_u64 v[100:101], v[92:93], 0, s[8:9]
	s_mov_b32 s8, 0xefe00200
	v_cvt_pk_bf16_f32 v102, v66, v67
	v_cvt_pk_bf16_f32 v103, v68, v69
	s_mov_b32 s9, -1
	global_store_dwordx2 v[100:101], v[102:103], off sc1
	s_nop 1
	v_lshl_add_u64 v[102:103], v[92:93], 0, s[8:9]
	s_mov_b32 s8, 0xefe00400
	s_mov_b32 s9, -1
	v_cvt_pk_bf16_f32 v100, v62, v63
	v_cvt_pk_bf16_f32 v101, v64, v65
	global_store_dwordx2 v[102:103], v[100:101], off sc1
	s_nop 1
	v_lshl_add_u64 v[102:103], v[92:93], 0, s[8:9]
	s_mov_b32 s8, 0xefe00600
	s_mov_b32 s9, -1
	v_cvt_pk_bf16_f32 v100, v42, v43
	v_cvt_pk_bf16_f32 v101, v44, v45
	global_store_dwordx2 v[102:103], v[100:101], off sc1
	s_nop 1
	v_lshl_add_u64 v[102:103], v[92:93], 0, s[8:9]
	s_mov_b32 s8, 0xefe00800
	s_mov_b32 s9, -1
	v_cvt_pk_bf16_f32 v100, v22, v23
	v_cvt_pk_bf16_f32 v101, v24, v25
	global_store_dwordx2 v[102:103], v[100:101], off sc1
	s_nop 1
	v_lshl_add_u64 v[102:103], v[92:93], 0, s[8:9]
	s_mov_b32 s8, 0xefe00a00
	s_mov_b32 s9, -1
	v_cvt_pk_bf16_f32 v100, v18, v19
	v_cvt_pk_bf16_f32 v101, v20, v21
	global_store_dwordx2 v[102:103], v[100:101], off sc1
	s_nop 1
	v_lshl_add_u64 v[102:103], v[92:93], 0, s[8:9]
	s_mov_b32 s8, 0xefe00c00
	s_mov_b32 s9, -1
	v_cvt_pk_bf16_f32 v100, v12, v13
	v_cvt_pk_bf16_f32 v101, v14, v15
	global_store_dwordx2 v[102:103], v[100:101], off sc1
	s_nop 1
	v_lshl_add_u64 v[102:103], v[92:93], 0, s[8:9]
	s_mov_b32 s8, 0xefe00e00
	v_cvt_pk_bf16_f32 v100, v8, v9
	v_cvt_pk_bf16_f32 v101, v10, v11
	global_store_dwordx2 v[102:103], v[100:101], off sc1
	s_nop 1
	s_mov_b32 s9, -1
	v_cvt_pk_bf16_f32 v100, v4, v5
	v_cvt_pk_bf16_f32 v101, v6, v7
	v_lshl_add_u64 v[102:103], v[92:93], 0, s[8:9]
	global_store_dwordx2 v[102:103], v[100:101], off sc1
	s_nop 1
	s_nop 0
	v_mul_f32_e32 v108, v4, v4
	v_mul_f32_e32 v110, v5, v5
	v_mul_f32_e32 v106, v6, v6
	v_mul_f32_e32 v104, v7, v7
	v_pk_add_f32 v[108:109], v[108:109], v[110:111]
	v_pk_add_f32 v[104:105], v[106:107], v[104:105]
	v_add_u32_e32 v70, 0x800, v70
	v_pk_add_f32 v[104:105], v[108:109], v[104:105]
	v_add_u32_e32 v94, 0x400000, v94
	v_add_f32_e32 v73, v104, v105
	ds_bpermute_b32 v77, v17, v73
	s_waitcnt lgkmcnt(0)
	v_add_f32_e32 v73, v73, v77
	ds_bpermute_b32 v77, v71, v73
	s_waitcnt lgkmcnt(0)
	v_add_f32_e32 v73, v73, v77
	ds_bpermute_b32 v77, v95, v73
	s_waitcnt lgkmcnt(0)
	v_add_f32_e32 v73, v73, v77
	ds_bpermute_b32 v77, v96, v73
	s_waitcnt lgkmcnt(0)
	v_add_f32_e32 v73, v73, v77
	ds_bpermute_b32 v77, v97, v73
	s_waitcnt lgkmcnt(0)
	v_add_f32_e32 v73, v73, v77
	ds_bpermute_b32 v77, v98, v73
	s_waitcnt lgkmcnt(0)
; __device__ __forceinline__ void store8_wt(void* p, u32x2w v) { asm volatile("global_store_dwordx2 %0, %1, off sc1\n\ts_nop 1" :: "v"(p), "v"(v) : "memory"); }
; __device__ __forceinline__ unsigned pk2(float lo, float hi) { f32x2_t v = {lo, hi}; bf16x2_t b = __builtin_convertvector(v, bf16x2_t); return __builtin_bit_cast(unsigned, b); }
; template <int MODE> __device__ __forceinline__ void norm_phase(const Ptrs& P, const float* nw, int gw, int NGW, int lane) {
;     ...
;         const float rstd = 1.0f / sqrtf(ss * (1.0f / DM) + EPS);
;         if (MODE == 1) {
; #pragma unroll
;             for (int j = 0; j < 8; ++j) { u32x2 w; w.x = pk2(v[j][0], v[j][1]); w.y = pk2(v[j][2], v[j][3]); pg8::store8_wt((u32x2*)(H + (size_t)row * DM) + 64 * j + lane, w); }
;         }
; #pragma unroll
;         for (int j = 0; j < 8; ++j) {
;             const f32x4 w4 = ((const f32x4*)nw)[64 * j + lane];
;             const f32x4 o = v[j] * rstd * w4;
;             if (MODE == 2) ((f32x4*)(P.out + (size_t)row * DM))[64 * j + lane] = o;
;             else { u32x2 w; w.x = pk2(o[0], o[1]); w.y = pk2(o[2], o[3]); pg8::store8_wt((u32x2*)(U + (size_t)row * DM) + 64 * j + lane, w); }
;         }
	v_add_f32_e32 v73, v73, v77
	v_fmamk_f32 v73, v73, 0x3a000000, v234
	v_mul_f32_e32 v77, 0x4f800000, v73
	v_cmp_gt_f32_e32 vcc, s17, v73
	s_nop 1
	v_cndmask_b32_e32 v73, v73, v77, vcc
	v_sqrt_f32_e32 v77, v73
	s_nop 0
	v_add_u32_e32 v79, -1, v77
	v_fma_f32 v81, -v79, v77, v73
	v_cmp_ge_f32_e64 s[36:37], 0, v81
	v_add_u32_e32 v81, 1, v77
	s_nop 0
	v_cndmask_b32_e64 v79, v77, v79, s[36:37]
	v_fma_f32 v77, -v81, v77, v73
	v_cmp_lt_f32_e64 s[36:37], 0, v77
	s_nop 1
	v_cndmask_b32_e64 v77, v79, v81, s[36:37]
	v_mul_f32_e32 v79, 0x37800000, v77
	v_cndmask_b32_e32 v77, v77, v79, vcc
	v_cmp_class_f32_e32 vcc, v73, v235
	s_nop 1
	v_cndmask_b32_e32 v73, v77, v73, vcc
	v_div_scale_f32 v77, s[8:9], v73, v73, 1.0
	v_rcp_f32_e32 v79, v77
	s_mov_b64 s[8:9], 0x200
	v_fma_f32 v81, -v77, v79, 1.0
	v_fmac_f32_e32 v79, v81, v79
	v_div_scale_f32 v81, vcc, 1.0, v73, 1.0
	v_mul_f32_e32 v83, v81, v79
	v_fma_f32 v99, -v77, v83, v81
	v_fmac_f32_e32 v83, v99, v79
	v_fma_f32 v77, -v77, v83, v81
	v_div_fmas_f32 v77, v77, v79, v83
	v_div_fixup_f32 v104, v77, v73, 1.0
	v_pk_mul_f32 v[66:67], v[66:67], v[104:105] op_sel_hi:[1,0]
	v_pk_mul_f32 v[68:69], v[68:69], v[104:105] op_sel_hi:[1,0]
	s_nop 0
	v_pk_mul_f32 v[66:67], v[66:67], v[128:129]
	v_pk_mul_f32 v[68:69], v[68:69], v[130:131]
	v_cvt_pk_bf16_f32 v66, v66, v67
	v_cvt_pk_bf16_f32 v67, v68, v69
	global_store_dwordx2 v[92:93], v[66:67], off sc1
	s_nop 1
	s_nop 0
	v_pk_mul_f32 v[62:63], v[62:63], v[104:105] op_sel_hi:[1,0]
	v_pk_mul_f32 v[64:65], v[64:65], v[104:105] op_sel_hi:[1,0]
	v_lshl_add_u64 v[100:101], v[92:93], 0, s[8:9]
	v_pk_mul_f32 v[42:43], v[42:43], v[104:105] op_sel_hi:[1,0]
	v_pk_mul_f32 v[44:45], v[44:45], v[104:105] op_sel_hi:[1,0]
	s_mov_b64 s[8:9], 0x400
	v_pk_mul_f32 v[22:23], v[22:23], v[104:105] op_sel_hi:[1,0]
	v_pk_mul_f32 v[24:25], v[24:25], v[104:105] op_sel_hi:[1,0]
	v_pk_mul_f32 v[18:19], v[18:19], v[104:105] op_sel_hi:[1,0]
	v_pk_mul_f32 v[20:21], v[20:21], v[104:105] op_sel_hi:[1,0]
	v_pk_mul_f32 v[12:13], v[12:13], v[104:105] op_sel_hi:[1,0]
	v_pk_mul_f32 v[14:15], v[14:15], v[104:105] op_sel_hi:[1,0]
	v_pk_mul_f32 v[8:9], v[8:9], v[104:105] op_sel_hi:[1,0]
	v_pk_mul_f32 v[10:11], v[10:11], v[104:105] op_sel_hi:[1,0]
	s_nop 0
	v_pk_mul_f32 v[64:65], v[64:65], v[134:135]
	v_pk_mul_f32 v[62:63], v[62:63], v[132:133]
	v_lshl_add_u64 v[66:67], v[92:93], 0, s[8:9]
	v_cvt_pk_bf16_f32 v62, v62, v63
	v_cvt_pk_bf16_f32 v63, v64, v65
	global_store_dwordx2 v[100:101], v[62:63], off sc1
	s_nop 1
	s_nop 0
	s_mov_b64 s[8:9], 0x600
	s_nop 0
	v_pk_mul_f32 v[44:45], v[44:45], v[138:139]
	v_pk_mul_f32 v[42:43], v[42:43], v[136:137]
	v_lshl_add_u64 v[62:63], v[92:93], 0, s[8:9]
	v_cvt_pk_bf16_f32 v42, v42, v43
	v_cvt_pk_bf16_f32 v43, v44, v45
	global_store_dwordx2 v[66:67], v[42:43], off sc1
	s_nop 1
	s_nop 0
	s_mov_b64 s[8:9], 0x800
	s_waitcnt vmcnt(11)
	v_mov_b64_e32 v[68:69], v[28:29]
	v_mov_b64_e32 v[66:67], v[26:27]
	s_nop 0
	v_pk_mul_f32 v[24:25], v[24:25], v[142:143]
	v_pk_mul_f32 v[22:23], v[22:23], v[140:141]
	v_lshl_add_u64 v[42:43], v[92:93], 0, s[8:9]
	v_cvt_pk_bf16_f32 v22, v22, v23
	v_cvt_pk_bf16_f32 v23, v24, v25
	global_store_dwordx2 v[62:63], v[22:23], off sc1
	s_nop 1
	s_nop 0
	s_mov_b64 s[8:9], 0xa00
	v_pk_mul_f32 v[44:45], v[4:5], v[104:105] op_sel_hi:[1,0]
	v_pk_mul_f32 v[62:63], v[6:7], v[104:105] op_sel_hi:[1,0]
	v_mov_b64_e32 v[4:5], v[58:59]
	v_mov_b64_e32 v[6:7], v[60:61]
	s_nop 0
	v_pk_mul_f32 v[20:21], v[20:21], v[146:147]
	v_pk_mul_f32 v[18:19], v[18:19], v[144:145]
	v_lshl_add_u64 v[22:23], v[92:93], 0, s[8:9]
	v_cvt_pk_bf16_f32 v18, v18, v19
	v_cvt_pk_bf16_f32 v19, v20, v21
	global_store_dwordx2 v[42:43], v[18:19], off sc1
	s_nop 1
	s_nop 0
	s_mov_b64 s[8:9], 0xc00
	s_nop 0
	v_pk_mul_f32 v[14:15], v[14:15], v[150:151]
	v_pk_mul_f32 v[12:13], v[12:13], v[148:149]
	v_lshl_add_u64 v[18:19], v[92:93], 0, s[8:9]
	v_cvt_pk_bf16_f32 v12, v12, v13
	v_cvt_pk_bf16_f32 v13, v14, v15
	global_store_dwordx2 v[22:23], v[12:13], off sc1
	s_nop 1
	s_nop 0
	s_mov_b64 s[8:9], 0xe00
	v_lshl_add_u64 v[42:43], v[92:93], 0, s[8:9]
	s_mov_b64 s[8:9], 0x1000000
	v_lshl_add_u64 v[0:1], v[0:1], 0, s[8:9]
	s_mov_b64 s[8:9], 0x800000
	v_lshl_add_u64 v[92:93], v[92:93], 0, s[8:9]
	s_nop 0
	v_pk_mul_f32 v[10:11], v[10:11], v[154:155]
	v_pk_mul_f32 v[8:9], v[8:9], v[152:153]
	v_mov_b64_e32 v[12:13], v[50:51]
	v_cvt_pk_bf16_f32 v8, v8, v9
	v_cvt_pk_bf16_f32 v9, v10, v11
	global_store_dwordx2 v[18:19], v[8:9], off sc1
	s_nop 1
	s_nop 0
	v_mov_b64_e32 v[8:9], v[54:55]
	v_mov_b64_e32 v[18:19], v[46:47]
	v_mov_b64_e32 v[10:11], v[56:57]
	v_mov_b64_e32 v[14:15], v[52:53]
	v_mov_b64_e32 v[20:21], v[48:49]
	s_nop 0
	v_pk_mul_f32 v[24:25], v[62:63], v[158:159]
	v_pk_mul_f32 v[22:23], v[44:45], v[156:157]
	v_mov_b64_e32 v[64:65], v[32:33]
	v_cvt_pk_bf16_f32 v22, v22, v23
	v_cvt_pk_bf16_f32 v23, v24, v25
	global_store_dwordx2 v[42:43], v[22:23], off sc1
	s_nop 1
	v_mov_b64_e32 v[22:23], v[38:39]
	v_mov_b64_e32 v[44:45], v[36:37]
	v_mov_b64_e32 v[24:25], v[40:41]
	v_mov_b64_e32 v[42:43], v[34:35]
	v_mov_b64_e32 v[62:63], v[30:31]
	s_andn2_b64 exec, exec, s[6:7]
	s_cbranch_execz .LBB0_157
